# P2(c): q/k loads (32 per thread) also issued in the unit prologue into spare registers; all 4 load groups in one round trip
# baseline (speedup 1.0000x reference)
.LBB0_242:
	s_or_b64 exec, exec, s[42:43]
	s_and_b32 s48, s47, 3
	v_add_u32_e32 v88, s44, v27
	v_mov_b64_e32 v[96:97], s[0:1]
	v_mad_i64_i32 v[88:89], s[42:43], v88, s35, v[96:97]
	s_mul_i32 s14, s48, 0x180
	v_lshl_add_u64 v[88:89], v[88:89], 0, s[14:15]
	v_add_u32_e32 v90, s44, v60
	v_lshl_add_u64 v[88:89], v[18:19], 1, v[88:89]
	v_mad_i64_i32 v[90:91], s[42:43], v90, s35, v[96:97]
	v_add_co_u32_e32 v88, vcc, 0x2000, v88
	v_lshl_add_u64 v[90:91], v[90:91], 0, s[14:15]
	s_nop 0
	v_addc_co_u32_e32 v89, vcc, 0, v89, vcc
	v_lshl_add_u64 v[90:91], v[20:21], 1, v[90:91]
	v_add_co_u32_e32 v92, vcc, 0x2000, v90
	v_add_u32_e32 v98, s44, v61
	s_nop 0
	v_addc_co_u32_e32 v93, vcc, 0, v91, vcc
	global_load_dwordx4 v[88:91], v[88:89], off offset:3584
	s_nop 0
	global_load_dwordx4 v[92:95], v[92:93], off offset:3584
	v_mad_i64_i32 v[96:97], s[42:43], v98, s35, v[96:97]
	v_lshl_add_u64 v[96:97], v[96:97], 0, s[14:15]
	v_lshl_add_u64 v[96:97], v[22:23], 1, v[96:97]
	v_add_co_u32_e32 v96, vcc, 0x2000, v96
	s_nop 1
	v_addc_co_u32_e32 v97, vcc, 0, v97, vcc
	global_load_dwordx4 v[96:99], v[96:97], off offset:3584
	s_and_saveexec_b64 s[44:45], s[4:5]
	s_cbranch_execz .Lp2_nog
	s_mul_i32 s14, s48, 0x60
	v_add_u32_e32 v2, s14, v24
	v_ashrrev_i32_e32 v3, 31, v2
	v_lshlrev_b64 v[42:43], 2, v[2:3]
	v_lshl_add_u64 v[44:45], s[10:11], 0, v[42:43]
	v_add_co_u32_e32 v10, vcc, 0x1000, v44
	global_load_dword v4, v[44:45], off
	global_load_dword v6, v[44:45], off offset:1536
	global_load_dword v2, v[44:45], off offset:3072
	v_addc_co_u32_e32 v11, vcc, 0, v45, vcc
	global_load_dword v8, v[10:11], off offset:512
	global_load_dword v5, v[10:11], off offset:2048
	global_load_dword v7, v[10:11], off offset:3584
	v_add_co_u32_e32 v10, vcc, s22, v44
	s_movk_i32 s14, 0x4000
	s_nop 0
	v_addc_co_u32_e32 v11, vcc, 0, v45, vcc
	global_load_dword v3, v[10:11], off offset:1024
	global_load_dword v9, v[10:11], off offset:2560
	v_add_co_u32_e32 v10, vcc, 0x3000, v44
	v_lshl_add_u64 v[42:43], s[24:25], 0, v[42:43]
	s_nop 0
	v_addc_co_u32_e32 v11, vcc, 0, v45, vcc
	v_add_co_u32_e32 v46, vcc, s14, v44
	global_load_dword v12, v[10:11], off
	global_load_dword v14, v[10:11], off offset:1536
	s_nop 0
	global_load_dword v10, v[10:11], off offset:3072
	v_addc_co_u32_e32 v47, vcc, 0, v45, vcc
	v_add_co_u32_e32 v44, vcc, 0x5000, v44
	global_load_dword v16, v[46:47], off offset:512
	global_load_dword v13, v[46:47], off offset:2048
	global_load_dword v15, v[46:47], off offset:3584
	v_addc_co_u32_e32 v45, vcc, 0, v45, vcc
	global_load_dword v11, v[44:45], off offset:1024
	global_load_dword v17, v[44:45], off offset:2560
	global_load_dword v42, v[42:43], off
	s_and_b32 s14, s47, 0xffffffc
	v_add_lshl_u32 v204, s14, v64, 4
	v_mov_b64_e32 v[202:203], s[0:1]
	v_mad_i64_i32 v[202:203], s[50:51], v204, s35, v[202:203]
	s_mul_i32 s14, s48, 0xc0
	v_lshl_add_u64 v[202:203], v[202:203], 0, s[14:15]
	v_lshl_add_u64 v[204:205], v[24:25], 1, v[202:203]
	v_add_co_u32_e32 v236, vcc, s22, v204
	s_movk_i32 s14, 0x6000
	s_nop 0
	v_addc_co_u32_e32 v237, vcc, 0, v205, vcc
	v_add_co_u32_e32 v234, vcc, s14, v204
	s_mov_b32 s14, 0x9000
	s_nop 0
	v_addc_co_u32_e32 v235, vcc, 0, v205, vcc
	v_add_co_u32_e32 v232, vcc, s14, v204
	s_mov_b32 s14, 0xd000
	s_nop 0
	v_addc_co_u32_e32 v233, vcc, 0, v205, vcc
	v_add_co_u32_e32 v230, vcc, s14, v204
	s_mov_b32 s14, 0x11000
	s_nop 0
	v_addc_co_u32_e32 v231, vcc, 0, v205, vcc
	v_add_co_u32_e32 v228, vcc, s14, v204
	s_mov_b32 s14, 0x14000
	s_nop 0
	v_addc_co_u32_e32 v229, vcc, 0, v205, vcc
	v_add_co_u32_e32 v226, vcc, s14, v204
	s_mov_b32 s14, 0x18000
	s_nop 0
	v_addc_co_u32_e32 v227, vcc, 0, v205, vcc
	v_add_co_u32_e32 v224, vcc, s14, v204
	s_mov_b32 s14, 0x1b000
	s_nop 0
	v_addc_co_u32_e32 v225, vcc, 0, v205, vcc
	v_add_co_u32_e32 v220, vcc, s14, v204
	s_mov_b32 s14, 0x1c000
	s_nop 0
	v_addc_co_u32_e32 v221, vcc, 0, v205, vcc
	v_add_co_u32_e32 v222, vcc, s14, v204
	s_mov_b32 s14, 0x1f000
	s_nop 0
	v_addc_co_u32_e32 v223, vcc, 0, v205, vcc
	v_add_co_u32_e32 v218, vcc, s14, v204
	s_mov_b32 s14, 0x23000
	s_nop 0
	v_addc_co_u32_e32 v219, vcc, 0, v205, vcc
	v_add_co_u32_e32 v216, vcc, s14, v204
	s_mov_b32 s14, 0x26000
	s_nop 0
	v_addc_co_u32_e32 v217, vcc, 0, v205, vcc
	v_add_co_u32_e32 v214, vcc, s14, v204
	s_mov_b32 s14, 0x2a000
	s_nop 0
	v_addc_co_u32_e32 v215, vcc, 0, v205, vcc
	v_add_co_u32_e32 v212, vcc, s14, v204
	s_mov_b32 s14, 0x2e000
	s_nop 0
	v_addc_co_u32_e32 v213, vcc, 0, v205, vcc
	v_add_co_u32_e32 v210, vcc, s14, v204
	s_mov_b32 s14, 0x31000
	s_nop 0
	v_addc_co_u32_e32 v211, vcc, 0, v205, vcc
	v_add_co_u32_e32 v208, vcc, s14, v204
	s_mov_b32 s14, 0x35000
	s_nop 0
	v_addc_co_u32_e32 v209, vcc, 0, v205, vcc
	v_add_co_u32_e32 v206, vcc, s14, v204
	s_mov_b32 s14, 0x38000
	s_nop 0
	v_addc_co_u32_e32 v207, vcc, 0, v205, vcc
	v_add_co_u32_e32 v202, vcc, s14, v204
	s_mov_b32 s14, 0x39000
	s_nop 0
	v_addc_co_u32_e32 v203, vcc, 0, v205, vcc
	v_add_co_u32_e32 v204, vcc, s14, v204
	global_load_ushort v144, v[236:237], off offset:2048
	global_load_ushort v145, v[236:237], off offset:2816
	global_load_ushort v146, v[234:235], off offset:512
	global_load_ushort v147, v[234:235], off offset:1280
	global_load_ushort v148, v[232:233], off offset:3072
	global_load_ushort v149, v[232:233], off offset:3840
	global_load_ushort v150, v[230:231], off offset:1536
	global_load_ushort v151, v[230:231], off offset:2304
	global_load_ushort v152, v[228:229], off
	global_load_ushort v153, v[228:229], off offset:768
	global_load_ushort v154, v[226:227], off offset:2560
	global_load_ushort v155, v[226:227], off offset:3328
	global_load_ushort v156, v[224:225], off offset:1024
	global_load_ushort v157, v[224:225], off offset:1792
	global_load_ushort v158, v[220:221], off offset:3584
	global_load_ushort v159, v[222:223], off offset:256
	global_load_ushort v178, v[218:219], off offset:2048
	global_load_ushort v179, v[218:219], off offset:2816
	global_load_ushort v180, v[216:217], off offset:512
	global_load_ushort v181, v[216:217], off offset:1280
	global_load_ushort v182, v[214:215], off offset:3072
	global_load_ushort v183, v[214:215], off offset:3840
	global_load_ushort v184, v[212:213], off offset:1536
	global_load_ushort v185, v[212:213], off offset:2304
	v_addc_co_u32_e32 v205, vcc, 0, v205, vcc
	global_load_ushort v186, v[210:211], off
	global_load_ushort v187, v[210:211], off offset:768
	global_load_ushort v188, v[208:209], off offset:2560
	global_load_ushort v189, v[208:209], off offset:3328
	global_load_ushort v190, v[206:207], off offset:1024
	global_load_ushort v191, v[206:207], off offset:1792
	global_load_ushort v238, v[202:203], off offset:3584
	global_load_ushort v239, v[204:205], off offset:256
	s_or_b64 exec, exec, s[44:45]
	s_waitcnt vmcnt(49)
	s_branch .Lp2_w

.Lp2_w:
	ds_write_b128 v68, v[88:91] offset:21504
	ds_write_b128 v69, v[92:95] offset:21504
	ds_write_b128 v70, v[96:99] offset:21504
	s_and_saveexec_b64 s[42:43], s[8:9]
	ds_write_b128 v63, v[102:105]
	s_or_b64 exec, exec, s[42:43]
	s_waitcnt lgkmcnt(0)
	s_barrier
	s_and_saveexec_b64 s[44:45], s[4:5]
	s_cbranch_execz .LBB0_244
	s_mov_b32 s14, 0x3d800000
	ds_read_b128 v[44:47], v65
	ds_read_b128 v[48:51], v65 offset:16
	ds_read_b128 v[52:55], v65 offset:32
	ds_read_b128 v[56:59], v65 offset:48
	s_waitcnt lgkmcnt(3)
	v_mov_b32_e32 v72, v44
	s_waitcnt lgkmcnt(2)
	v_mov_b32_e32 v73, v48
	v_mov_b32_e32 v48, v45
	s_waitcnt vmcnt(43)
	v_pk_mul_f32 v[44:45], v[6:7], v[48:49]
	s_nop 0
	v_pk_fma_f32 v[44:45], v[4:5], v[72:73], v[44:45]
	v_mov_b32_e32 v48, v46
	v_mov_b32_e32 v49, v50
	v_mov_b32_e32 v50, v47
	s_waitcnt vmcnt(42)
	v_pk_fma_f32 v[44:45], v[2:3], v[48:49], v[44:45]
	s_waitcnt vmcnt(41)
	v_pk_fma_f32 v[44:45], v[8:9], v[50:51], v[44:45]
	s_waitcnt vmcnt(32)
	v_add_f32_e32 v43, v42, v44
	v_add_f32_e32 v43, v43, v45
	s_waitcnt lgkmcnt(0)
	v_mov_b32_e32 v45, v56
	v_mov_b32_e32 v56, v53
	v_mov_b32_e32 v44, v52
	v_pk_mul_f32 v[46:47], v[14:15], v[56:57]
	s_nop 0
	v_pk_fma_f32 v[44:45], v[12:13], v[44:45], v[46:47]
	v_mov_b32_e32 v46, v54
	v_mov_b32_e32 v47, v58
	v_pk_fma_f32 v[44:45], v[10:11], v[46:47], v[44:45]
	v_mov_b32_e32 v58, v55
	v_pk_fma_f32 v[44:45], v[16:17], v[58:59], v[44:45]
	s_nop 0
	v_add_f32_e32 v43, v43, v44
	v_add_f32_e32 v43, v43, v45
	v_min_f32_e32 v44, 0, v43
	v_mul_f32_e64 v43, |v43|, s82
	v_exp_f32_e32 v43, v43
	s_nop 0
	v_add_f32_e32 v43, 1.0, v43
	v_cmp_gt_f32_e32 vcc, s2, v43
	s_nop 1
	v_cndmask_b32_e64 v45, 0, 32, vcc
	v_ldexp_f32 v43, v43, v45
	v_log_f32_e32 v43, v43
	s_nop 0
	v_mul_f32_e32 v45, 0x3f317217, v43
	v_fma_f32 v45, v43, s85, -v45
	v_fmac_f32_e32 v45, 0x3377d1cf, v43
	v_fmac_f32_e32 v45, 0x3f317217, v43
	v_cmp_lt_f32_e64 s[42:43], |v43|, s83
	s_nop 1
	v_cndmask_b32_e64 v43, v43, v45, s[42:43]
	v_cndmask_b32_e32 v45, 0, v200, vcc
	v_sub_f32_e32 v43, v43, v45
	v_sub_f32_e32 v43, v44, v43
	ds_read_b128 v[44:47], v65 offset:64
	ds_read_b128 v[48:51], v65 offset:80
	v_fma_f32 v72, v43, s14, 0
	s_waitcnt lgkmcnt(1)
	v_mov_b32_e32 v52, v44
	s_waitcnt lgkmcnt(0)
	v_mov_b32_e32 v53, v48
	v_mov_b32_e32 v48, v45
	v_pk_mul_f32 v[44:45], v[6:7], v[48:49]
	v_mov_b32_e32 v48, v46
	v_pk_fma_f32 v[44:45], v[4:5], v[52:53], v[44:45]
	v_mov_b32_e32 v49, v50
	v_pk_fma_f32 v[44:45], v[2:3], v[48:49], v[44:45]
	v_mov_b32_e32 v50, v47
	v_pk_fma_f32 v[44:45], v[8:9], v[50:51], v[44:45]
	s_nop 0
	v_add_f32_e32 v43, v42, v44
	v_add_f32_e32 v43, v43, v45
	ds_read_b128 v[44:47], v65 offset:96
	ds_read_b128 v[48:51], v65 offset:112
	s_waitcnt lgkmcnt(1)
	v_mov_b32_e32 v52, v44
	s_waitcnt lgkmcnt(0)
	v_mov_b32_e32 v53, v48
	v_mov_b32_e32 v48, v45
	v_pk_mul_f32 v[44:45], v[14:15], v[48:49]
	v_mov_b32_e32 v48, v46
	v_pk_fma_f32 v[44:45], v[12:13], v[52:53], v[44:45]
	v_mov_b32_e32 v49, v50
	v_pk_fma_f32 v[44:45], v[10:11], v[48:49], v[44:45]
	v_mov_b32_e32 v50, v47
	v_pk_fma_f32 v[44:45], v[16:17], v[50:51], v[44:45]
	s_nop 0
	v_add_f32_e32 v43, v43, v44
	v_add_f32_e32 v43, v43, v45
	v_min_f32_e32 v44, 0, v43
	v_mul_f32_e64 v43, |v43|, s82
	v_exp_f32_e32 v43, v43
	s_nop 0
	v_add_f32_e32 v43, 1.0, v43
	v_cmp_gt_f32_e32 vcc, s2, v43
	s_nop 1
	v_cndmask_b32_e64 v45, 0, 32, vcc
	v_ldexp_f32 v43, v43, v45
	v_log_f32_e32 v43, v43
	s_nop 0
	v_mul_f32_e32 v45, 0x3f317217, v43
	v_fma_f32 v45, v43, s85, -v45
	v_fmac_f32_e32 v45, 0x3377d1cf, v43
	v_fmac_f32_e32 v45, 0x3f317217, v43
	v_cmp_lt_f32_e64 s[42:43], |v43|, s83
	s_nop 1
	v_cndmask_b32_e64 v43, v43, v45, s[42:43]
	v_cndmask_b32_e32 v45, 0, v200, vcc
	v_sub_f32_e32 v43, v43, v45
	v_sub_f32_e32 v43, v44, v43
	ds_read_b128 v[44:47], v65 offset:128
	ds_read_b128 v[48:51], v65 offset:144
	v_fmamk_f32 v73, v43, 0x3d800000, v72
	s_waitcnt lgkmcnt(1)
	v_mov_b32_e32 v52, v44
	s_waitcnt lgkmcnt(0)
	v_mov_b32_e32 v53, v48
	v_mov_b32_e32 v48, v45
	v_pk_mul_f32 v[44:45], v[6:7], v[48:49]
	v_mov_b32_e32 v48, v46
	v_pk_fma_f32 v[44:45], v[4:5], v[52:53], v[44:45]
	v_mov_b32_e32 v49, v50
	v_pk_fma_f32 v[44:45], v[2:3], v[48:49], v[44:45]
	v_mov_b32_e32 v50, v47
	v_pk_fma_f32 v[44:45], v[8:9], v[50:51], v[44:45]
	s_nop 0
	v_add_f32_e32 v43, v42, v44
	v_add_f32_e32 v43, v43, v45
	ds_read_b128 v[44:47], v65 offset:160
	ds_read_b128 v[48:51], v65 offset:176
	s_waitcnt lgkmcnt(1)
	v_mov_b32_e32 v52, v44
	s_waitcnt lgkmcnt(0)
	v_mov_b32_e32 v53, v48
	v_mov_b32_e32 v48, v45
	v_pk_mul_f32 v[44:45], v[14:15], v[48:49]
	v_mov_b32_e32 v48, v46
	v_pk_fma_f32 v[44:45], v[12:13], v[52:53], v[44:45]
	v_mov_b32_e32 v49, v50
	v_pk_fma_f32 v[44:45], v[10:11], v[48:49], v[44:45]
	v_mov_b32_e32 v50, v47
	v_pk_fma_f32 v[44:45], v[16:17], v[50:51], v[44:45]
	s_nop 0
	v_add_f32_e32 v43, v43, v44
	v_add_f32_e32 v43, v43, v45
	v_min_f32_e32 v44, 0, v43
	v_mul_f32_e64 v43, |v43|, s82
	v_exp_f32_e32 v43, v43
	s_nop 0
	v_add_f32_e32 v43, 1.0, v43
	v_cmp_gt_f32_e32 vcc, s2, v43
	s_nop 1
	v_cndmask_b32_e64 v45, 0, 32, vcc
	v_ldexp_f32 v43, v43, v45
	v_log_f32_e32 v43, v43
	s_nop 0
	v_mul_f32_e32 v45, 0x3f317217, v43
	v_fma_f32 v45, v43, s85, -v45
	v_fmac_f32_e32 v45, 0x3377d1cf, v43
	v_fmac_f32_e32 v45, 0x3f317217, v43
	v_cmp_lt_f32_e64 s[42:43], |v43|, s83
	s_nop 1
	v_cndmask_b32_e64 v43, v43, v45, s[42:43]
	v_cndmask_b32_e32 v45, 0, v200, vcc
	v_sub_f32_e32 v43, v43, v45
	v_sub_f32_e32 v43, v44, v43
	ds_read_b128 v[44:47], v65 offset:192
	ds_read_b128 v[48:51], v65 offset:208
	v_fmamk_f32 v74, v43, 0x3d800000, v73
	s_waitcnt lgkmcnt(1)
	v_mov_b32_e32 v52, v44
	s_waitcnt lgkmcnt(0)
	v_mov_b32_e32 v53, v48
	v_mov_b32_e32 v48, v45
	v_pk_mul_f32 v[44:45], v[6:7], v[48:49]
	v_mov_b32_e32 v48, v46
	v_pk_fma_f32 v[44:45], v[4:5], v[52:53], v[44:45]
	v_mov_b32_e32 v49, v50
	v_pk_fma_f32 v[44:45], v[2:3], v[48:49], v[44:45]
	v_mov_b32_e32 v50, v47
	v_pk_fma_f32 v[44:45], v[8:9], v[50:51], v[44:45]
	s_nop 0
	v_add_f32_e32 v43, v42, v44
	v_add_f32_e32 v43, v43, v45
	ds_read_b128 v[44:47], v65 offset:224
	ds_read_b128 v[48:51], v65 offset:240
	s_waitcnt lgkmcnt(1)
	v_mov_b32_e32 v52, v44
	s_waitcnt lgkmcnt(0)
	v_mov_b32_e32 v53, v48
	v_mov_b32_e32 v48, v45
	v_pk_mul_f32 v[44:45], v[14:15], v[48:49]
	v_mov_b32_e32 v48, v46
	v_pk_fma_f32 v[44:45], v[12:13], v[52:53], v[44:45]
	v_mov_b32_e32 v49, v50
	v_pk_fma_f32 v[44:45], v[10:11], v[48:49], v[44:45]
	v_mov_b32_e32 v50, v47
	v_pk_fma_f32 v[44:45], v[16:17], v[50:51], v[44:45]
	s_nop 0
	v_add_f32_e32 v43, v43, v44
	v_add_f32_e32 v43, v43, v45
	v_min_f32_e32 v44, 0, v43
	v_mul_f32_e64 v43, |v43|, s82
	v_exp_f32_e32 v43, v43
	s_nop 0
	v_add_f32_e32 v43, 1.0, v43
	v_cmp_gt_f32_e32 vcc, s2, v43
	s_nop 1
	v_cndmask_b32_e64 v45, 0, 32, vcc
	v_ldexp_f32 v43, v43, v45
	v_log_f32_e32 v43, v43
	s_nop 0
	v_mul_f32_e32 v45, 0x3f317217, v43
	v_fma_f32 v45, v43, s85, -v45
	v_fmac_f32_e32 v45, 0x3377d1cf, v43
	v_fmac_f32_e32 v45, 0x3f317217, v43
	v_cmp_lt_f32_e64 s[42:43], |v43|, s83
	s_nop 1
	v_cndmask_b32_e64 v43, v43, v45, s[42:43]
	v_cndmask_b32_e32 v45, 0, v200, vcc
	v_sub_f32_e32 v43, v43, v45
	v_sub_f32_e32 v43, v44, v43
	ds_read_b128 v[44:47], v65 offset:256
	ds_read_b128 v[48:51], v65 offset:272
	v_fmamk_f32 v75, v43, 0x3d800000, v74
	s_waitcnt lgkmcnt(1)
	v_mov_b32_e32 v52, v44
	s_waitcnt lgkmcnt(0)
	v_mov_b32_e32 v53, v48
	v_mov_b32_e32 v48, v45
	v_pk_mul_f32 v[44:45], v[6:7], v[48:49]
	v_mov_b32_e32 v48, v46
	v_pk_fma_f32 v[44:45], v[4:5], v[52:53], v[44:45]
	v_mov_b32_e32 v49, v50
	v_pk_fma_f32 v[44:45], v[2:3], v[48:49], v[44:45]
	v_mov_b32_e32 v50, v47
	v_pk_fma_f32 v[44:45], v[8:9], v[50:51], v[44:45]
	s_nop 0
	v_add_f32_e32 v43, v42, v44
	v_add_f32_e32 v43, v43, v45
	ds_read_b128 v[44:47], v65 offset:288
	ds_read_b128 v[48:51], v65 offset:304
	s_waitcnt lgkmcnt(1)
	v_mov_b32_e32 v52, v44
	s_waitcnt lgkmcnt(0)
	v_mov_b32_e32 v53, v48
	v_mov_b32_e32 v48, v45
	v_pk_mul_f32 v[44:45], v[14:15], v[48:49]
	v_mov_b32_e32 v48, v46
	v_pk_fma_f32 v[44:45], v[12:13], v[52:53], v[44:45]
	v_mov_b32_e32 v49, v50
	v_pk_fma_f32 v[44:45], v[10:11], v[48:49], v[44:45]
	v_mov_b32_e32 v50, v47
	v_pk_fma_f32 v[44:45], v[16:17], v[50:51], v[44:45]
	s_nop 0
	v_add_f32_e32 v43, v43, v44
	v_add_f32_e32 v43, v43, v45
	v_min_f32_e32 v44, 0, v43
	v_mul_f32_e64 v43, |v43|, s82
	v_exp_f32_e32 v43, v43
	s_nop 0
	v_add_f32_e32 v43, 1.0, v43
	v_cmp_gt_f32_e32 vcc, s2, v43
	s_nop 1
	v_cndmask_b32_e64 v45, 0, 32, vcc
	v_ldexp_f32 v43, v43, v45
	v_log_f32_e32 v43, v43
	s_nop 0
	v_mul_f32_e32 v45, 0x3f317217, v43
	v_fma_f32 v45, v43, s85, -v45
	v_fmac_f32_e32 v45, 0x3377d1cf, v43
	v_fmac_f32_e32 v45, 0x3f317217, v43
	v_cmp_lt_f32_e64 s[42:43], |v43|, s83
	s_nop 1
	v_cndmask_b32_e64 v43, v43, v45, s[42:43]
	v_cndmask_b32_e32 v45, 0, v200, vcc
	v_sub_f32_e32 v43, v43, v45
	v_sub_f32_e32 v43, v44, v43
	ds_read_b128 v[44:47], v65 offset:320
	ds_read_b128 v[48:51], v65 offset:336
	v_fmamk_f32 v76, v43, 0x3d800000, v75
	s_waitcnt lgkmcnt(1)
	v_mov_b32_e32 v52, v44
	s_waitcnt lgkmcnt(0)
	v_mov_b32_e32 v53, v48
	v_mov_b32_e32 v48, v45
	v_pk_mul_f32 v[44:45], v[6:7], v[48:49]
	v_mov_b32_e32 v48, v46
	v_pk_fma_f32 v[44:45], v[4:5], v[52:53], v[44:45]
	v_mov_b32_e32 v49, v50
	v_pk_fma_f32 v[44:45], v[2:3], v[48:49], v[44:45]
	v_mov_b32_e32 v50, v47
	v_pk_fma_f32 v[44:45], v[8:9], v[50:51], v[44:45]
	s_nop 0
	v_add_f32_e32 v43, v42, v44
	v_add_f32_e32 v43, v43, v45
	ds_read_b128 v[44:47], v65 offset:352
	ds_read_b128 v[48:51], v65 offset:368
	s_waitcnt lgkmcnt(1)
	v_mov_b32_e32 v52, v44
	s_waitcnt lgkmcnt(0)
	v_mov_b32_e32 v53, v48
	v_mov_b32_e32 v48, v45
	v_pk_mul_f32 v[44:45], v[14:15], v[48:49]
	v_mov_b32_e32 v48, v46
	v_pk_fma_f32 v[44:45], v[12:13], v[52:53], v[44:45]
	v_mov_b32_e32 v49, v50
	v_pk_fma_f32 v[44:45], v[10:11], v[48:49], v[44:45]
	v_mov_b32_e32 v50, v47
	v_pk_fma_f32 v[44:45], v[16:17], v[50:51], v[44:45]
	s_nop 0
	v_add_f32_e32 v43, v43, v44
	v_add_f32_e32 v43, v43, v45
	v_min_f32_e32 v44, 0, v43
	v_mul_f32_e64 v43, |v43|, s82
	v_exp_f32_e32 v43, v43
	s_nop 0
	v_add_f32_e32 v43, 1.0, v43
	v_cmp_gt_f32_e32 vcc, s2, v43
	s_nop 1
	v_cndmask_b32_e64 v45, 0, 32, vcc
	v_ldexp_f32 v43, v43, v45
	v_log_f32_e32 v43, v43
	s_nop 0
	v_mul_f32_e32 v45, 0x3f317217, v43
	v_fma_f32 v45, v43, s85, -v45
	v_fmac_f32_e32 v45, 0x3377d1cf, v43
	v_fmac_f32_e32 v45, 0x3f317217, v43
	v_cmp_lt_f32_e64 s[42:43], |v43|, s83
	s_nop 1
	v_cndmask_b32_e64 v43, v43, v45, s[42:43]
	v_cndmask_b32_e32 v45, 0, v200, vcc
	v_sub_f32_e32 v43, v43, v45
	v_sub_f32_e32 v43, v44, v43
	ds_read_b128 v[44:47], v65 offset:384
	ds_read_b128 v[48:51], v65 offset:400
	v_fmamk_f32 v77, v43, 0x3d800000, v76
	s_waitcnt lgkmcnt(1)
	v_mov_b32_e32 v52, v44
	s_waitcnt lgkmcnt(0)
	v_mov_b32_e32 v53, v48
	v_mov_b32_e32 v48, v45
	v_pk_mul_f32 v[44:45], v[6:7], v[48:49]
	v_mov_b32_e32 v48, v46
	v_pk_fma_f32 v[44:45], v[4:5], v[52:53], v[44:45]
	v_mov_b32_e32 v49, v50
	v_pk_fma_f32 v[44:45], v[2:3], v[48:49], v[44:45]
	v_mov_b32_e32 v50, v47
	v_pk_fma_f32 v[44:45], v[8:9], v[50:51], v[44:45]
	s_nop 0
	v_add_f32_e32 v43, v42, v44
	v_add_f32_e32 v43, v43, v45
	ds_read_b128 v[44:47], v65 offset:416
	ds_read_b128 v[48:51], v65 offset:432
	s_waitcnt lgkmcnt(1)
	v_mov_b32_e32 v52, v44
	s_waitcnt lgkmcnt(0)
	v_mov_b32_e32 v53, v48
	v_mov_b32_e32 v48, v45
	v_pk_mul_f32 v[44:45], v[14:15], v[48:49]
	v_mov_b32_e32 v48, v46
	v_pk_fma_f32 v[44:45], v[12:13], v[52:53], v[44:45]
	v_mov_b32_e32 v49, v50
	v_pk_fma_f32 v[44:45], v[10:11], v[48:49], v[44:45]
	v_mov_b32_e32 v50, v47
	v_pk_fma_f32 v[44:45], v[16:17], v[50:51], v[44:45]
	s_nop 0
	v_add_f32_e32 v43, v43, v44
	v_add_f32_e32 v43, v43, v45
	v_min_f32_e32 v44, 0, v43
	v_mul_f32_e64 v43, |v43|, s82
	v_exp_f32_e32 v43, v43
	s_nop 0
	v_add_f32_e32 v43, 1.0, v43
	v_cmp_gt_f32_e32 vcc, s2, v43
	s_nop 1
	v_cndmask_b32_e64 v45, 0, 32, vcc
	v_ldexp_f32 v43, v43, v45
	v_log_f32_e32 v43, v43
	s_nop 0
	v_mul_f32_e32 v45, 0x3f317217, v43
	v_fma_f32 v45, v43, s85, -v45
	v_fmac_f32_e32 v45, 0x3377d1cf, v43
	v_fmac_f32_e32 v45, 0x3f317217, v43
	v_cmp_lt_f32_e64 s[42:43], |v43|, s83
	s_nop 1
	v_cndmask_b32_e64 v43, v43, v45, s[42:43]
	v_cndmask_b32_e32 v45, 0, v200, vcc
	v_sub_f32_e32 v43, v43, v45
	v_sub_f32_e32 v43, v44, v43
	ds_read_b128 v[44:47], v65 offset:448
	ds_read_b128 v[48:51], v65 offset:464
	v_fmamk_f32 v78, v43, 0x3d800000, v77
	s_waitcnt lgkmcnt(1)
	v_mov_b32_e32 v52, v44
	s_waitcnt lgkmcnt(0)
	v_mov_b32_e32 v53, v48
	v_mov_b32_e32 v48, v45
	v_pk_mul_f32 v[44:45], v[6:7], v[48:49]
	v_mov_b32_e32 v48, v46
	v_pk_fma_f32 v[44:45], v[4:5], v[52:53], v[44:45]
	v_mov_b32_e32 v49, v50
	v_pk_fma_f32 v[44:45], v[2:3], v[48:49], v[44:45]
	v_mov_b32_e32 v50, v47
	v_pk_fma_f32 v[44:45], v[8:9], v[50:51], v[44:45]
	s_nop 0
	v_add_f32_e32 v43, v42, v44
	v_add_f32_e32 v43, v43, v45
	ds_read_b128 v[44:47], v65 offset:480
	ds_read_b128 v[48:51], v65 offset:496
	s_waitcnt lgkmcnt(1)
	v_mov_b32_e32 v52, v44
	s_waitcnt lgkmcnt(0)
	v_mov_b32_e32 v53, v48
	v_mov_b32_e32 v48, v45
	v_pk_mul_f32 v[44:45], v[14:15], v[48:49]
	v_mov_b32_e32 v48, v46
	v_pk_fma_f32 v[44:45], v[12:13], v[52:53], v[44:45]
	v_mov_b32_e32 v49, v50
	v_pk_fma_f32 v[44:45], v[10:11], v[48:49], v[44:45]
	v_mov_b32_e32 v50, v47
	v_pk_fma_f32 v[44:45], v[16:17], v[50:51], v[44:45]
	s_nop 0
	v_add_f32_e32 v43, v43, v44
	v_add_f32_e32 v43, v43, v45
	v_min_f32_e32 v44, 0, v43
	v_mul_f32_e64 v43, |v43|, s82
	v_exp_f32_e32 v43, v43
	s_nop 0
	v_add_f32_e32 v43, 1.0, v43
	v_cmp_gt_f32_e32 vcc, s2, v43
	s_nop 1
	v_cndmask_b32_e64 v45, 0, 32, vcc
	v_ldexp_f32 v43, v43, v45
	v_log_f32_e32 v43, v43
	s_nop 0
	v_mul_f32_e32 v45, 0x3f317217, v43
	v_fma_f32 v45, v43, s85, -v45
	v_fmac_f32_e32 v45, 0x3377d1cf, v43
	v_fmac_f32_e32 v45, 0x3f317217, v43
	v_cmp_lt_f32_e64 s[42:43], |v43|, s83
	s_nop 1
	v_cndmask_b32_e64 v43, v43, v45, s[42:43]
	v_cndmask_b32_e32 v45, 0, v200, vcc
	v_sub_f32_e32 v43, v43, v45
	v_sub_f32_e32 v43, v44, v43
	ds_read_b128 v[44:47], v65 offset:512
	ds_read_b128 v[48:51], v65 offset:528
	v_fmamk_f32 v79, v43, 0x3d800000, v78
	s_waitcnt lgkmcnt(1)
	v_mov_b32_e32 v52, v44
	s_waitcnt lgkmcnt(0)
	v_mov_b32_e32 v53, v48
	v_mov_b32_e32 v48, v45
	v_pk_mul_f32 v[44:45], v[6:7], v[48:49]
	v_mov_b32_e32 v48, v46
	v_pk_fma_f32 v[44:45], v[4:5], v[52:53], v[44:45]
	v_mov_b32_e32 v49, v50
	v_pk_fma_f32 v[44:45], v[2:3], v[48:49], v[44:45]
	v_mov_b32_e32 v50, v47
	v_pk_fma_f32 v[44:45], v[8:9], v[50:51], v[44:45]
	s_nop 0
	v_add_f32_e32 v43, v42, v44
	v_add_f32_e32 v43, v43, v45
	ds_read_b128 v[44:47], v65 offset:544
	ds_read_b128 v[48:51], v65 offset:560
	s_waitcnt lgkmcnt(1)
	v_mov_b32_e32 v52, v44
	s_waitcnt lgkmcnt(0)
	v_mov_b32_e32 v53, v48
	v_mov_b32_e32 v48, v45
	v_pk_mul_f32 v[44:45], v[14:15], v[48:49]
	v_mov_b32_e32 v48, v46
	v_pk_fma_f32 v[44:45], v[12:13], v[52:53], v[44:45]
	v_mov_b32_e32 v49, v50
	v_pk_fma_f32 v[44:45], v[10:11], v[48:49], v[44:45]
	v_mov_b32_e32 v50, v47
	v_pk_fma_f32 v[44:45], v[16:17], v[50:51], v[44:45]
	s_nop 0
	v_add_f32_e32 v43, v43, v44
	v_add_f32_e32 v43, v43, v45
	v_min_f32_e32 v44, 0, v43
	v_mul_f32_e64 v43, |v43|, s82
	v_exp_f32_e32 v43, v43
	s_nop 0
	v_add_f32_e32 v43, 1.0, v43
	v_cmp_gt_f32_e32 vcc, s2, v43
	s_nop 1
	v_cndmask_b32_e64 v45, 0, 32, vcc
	v_ldexp_f32 v43, v43, v45
	v_log_f32_e32 v43, v43
	s_nop 0
	v_mul_f32_e32 v45, 0x3f317217, v43
	v_fma_f32 v45, v43, s85, -v45
	v_fmac_f32_e32 v45, 0x3377d1cf, v43
	v_fmac_f32_e32 v45, 0x3f317217, v43
	v_cmp_lt_f32_e64 s[42:43], |v43|, s83
	s_nop 1
	v_cndmask_b32_e64 v43, v43, v45, s[42:43]
	v_cndmask_b32_e32 v45, 0, v200, vcc
	v_sub_f32_e32 v43, v43, v45
	v_sub_f32_e32 v43, v44, v43
	ds_read_b128 v[44:47], v65 offset:576
	ds_read_b128 v[48:51], v65 offset:592
	v_fmamk_f32 v80, v43, 0x3d800000, v79
	s_waitcnt lgkmcnt(1)
	v_mov_b32_e32 v52, v44
	s_waitcnt lgkmcnt(0)
	v_mov_b32_e32 v53, v48
	v_mov_b32_e32 v48, v45
	v_pk_mul_f32 v[44:45], v[6:7], v[48:49]
	v_mov_b32_e32 v48, v46
	v_pk_fma_f32 v[44:45], v[4:5], v[52:53], v[44:45]
	v_mov_b32_e32 v49, v50
	v_pk_fma_f32 v[44:45], v[2:3], v[48:49], v[44:45]
	v_mov_b32_e32 v50, v47
	v_pk_fma_f32 v[44:45], v[8:9], v[50:51], v[44:45]
	s_nop 0
	v_add_f32_e32 v43, v42, v44
	v_add_f32_e32 v43, v43, v45
	ds_read_b128 v[44:47], v65 offset:608
	ds_read_b128 v[48:51], v65 offset:624
	s_waitcnt lgkmcnt(1)
	v_mov_b32_e32 v52, v44
	s_waitcnt lgkmcnt(0)
	v_mov_b32_e32 v53, v48
	v_mov_b32_e32 v48, v45
	v_pk_mul_f32 v[44:45], v[14:15], v[48:49]
	v_mov_b32_e32 v48, v46
	v_pk_fma_f32 v[44:45], v[12:13], v[52:53], v[44:45]
	v_mov_b32_e32 v49, v50
	v_pk_fma_f32 v[44:45], v[10:11], v[48:49], v[44:45]
	v_mov_b32_e32 v50, v47
	v_pk_fma_f32 v[44:45], v[16:17], v[50:51], v[44:45]
	s_nop 0
	v_add_f32_e32 v43, v43, v44
	v_add_f32_e32 v43, v43, v45
	v_min_f32_e32 v44, 0, v43
	v_mul_f32_e64 v43, |v43|, s82
	v_exp_f32_e32 v43, v43
	s_nop 0
	v_add_f32_e32 v43, 1.0, v43
	v_cmp_gt_f32_e32 vcc, s2, v43
	s_nop 1
	v_cndmask_b32_e64 v45, 0, 32, vcc
	v_ldexp_f32 v43, v43, v45
	v_log_f32_e32 v43, v43
	s_nop 0
	v_mul_f32_e32 v45, 0x3f317217, v43
	v_fma_f32 v45, v43, s85, -v45
	v_fmac_f32_e32 v45, 0x3377d1cf, v43
	v_fmac_f32_e32 v45, 0x3f317217, v43
	v_cmp_lt_f32_e64 s[42:43], |v43|, s83
	s_nop 1
	v_cndmask_b32_e64 v43, v43, v45, s[42:43]
	v_cndmask_b32_e32 v45, 0, v200, vcc
	v_sub_f32_e32 v43, v43, v45
	v_sub_f32_e32 v43, v44, v43
	ds_read_b128 v[44:47], v65 offset:640
	ds_read_b128 v[48:51], v65 offset:656
	v_fmamk_f32 v81, v43, 0x3d800000, v80
	s_waitcnt lgkmcnt(1)
	v_mov_b32_e32 v52, v44
	s_waitcnt lgkmcnt(0)
	v_mov_b32_e32 v53, v48
	v_mov_b32_e32 v48, v45
	v_pk_mul_f32 v[44:45], v[6:7], v[48:49]
	v_mov_b32_e32 v48, v46
	v_pk_fma_f32 v[44:45], v[4:5], v[52:53], v[44:45]
	v_mov_b32_e32 v49, v50
	v_pk_fma_f32 v[44:45], v[2:3], v[48:49], v[44:45]
	v_mov_b32_e32 v50, v47
	v_pk_fma_f32 v[44:45], v[8:9], v[50:51], v[44:45]
	s_nop 0
	v_add_f32_e32 v43, v42, v44
	v_add_f32_e32 v43, v43, v45
	ds_read_b128 v[44:47], v65 offset:672
	ds_read_b128 v[48:51], v65 offset:688
	s_waitcnt lgkmcnt(1)
	v_mov_b32_e32 v52, v44
	s_waitcnt lgkmcnt(0)
	v_mov_b32_e32 v53, v48
	v_mov_b32_e32 v48, v45
	v_pk_mul_f32 v[44:45], v[14:15], v[48:49]
	v_mov_b32_e32 v48, v46
	v_pk_fma_f32 v[44:45], v[12:13], v[52:53], v[44:45]
	v_mov_b32_e32 v49, v50
	v_pk_fma_f32 v[44:45], v[10:11], v[48:49], v[44:45]
	v_mov_b32_e32 v50, v47
	v_pk_fma_f32 v[44:45], v[16:17], v[50:51], v[44:45]
	s_nop 0
	v_add_f32_e32 v43, v43, v44
	v_add_f32_e32 v43, v43, v45
	v_min_f32_e32 v44, 0, v43
	v_mul_f32_e64 v43, |v43|, s82
	v_exp_f32_e32 v43, v43
	s_nop 0
	v_add_f32_e32 v43, 1.0, v43
	v_cmp_gt_f32_e32 vcc, s2, v43
	s_nop 1
	v_cndmask_b32_e64 v45, 0, 32, vcc
	v_ldexp_f32 v43, v43, v45
	v_log_f32_e32 v43, v43
	s_nop 0
	v_mul_f32_e32 v45, 0x3f317217, v43
	v_fma_f32 v45, v43, s85, -v45
	v_fmac_f32_e32 v45, 0x3377d1cf, v43
	v_fmac_f32_e32 v45, 0x3f317217, v43
	v_cmp_lt_f32_e64 s[42:43], |v43|, s83
	s_nop 1
	v_cndmask_b32_e64 v43, v43, v45, s[42:43]
	v_cndmask_b32_e32 v45, 0, v200, vcc
	v_sub_f32_e32 v43, v43, v45
	v_sub_f32_e32 v43, v44, v43
	ds_read_b128 v[44:47], v65 offset:704
	ds_read_b128 v[48:51], v65 offset:720
	v_fmamk_f32 v82, v43, 0x3d800000, v81
	s_waitcnt lgkmcnt(1)
	v_mov_b32_e32 v52, v44
	s_waitcnt lgkmcnt(0)
	v_mov_b32_e32 v53, v48
	v_mov_b32_e32 v48, v45
	v_pk_mul_f32 v[44:45], v[6:7], v[48:49]
	v_mov_b32_e32 v48, v46
	v_pk_fma_f32 v[44:45], v[4:5], v[52:53], v[44:45]
	v_mov_b32_e32 v49, v50
	v_pk_fma_f32 v[44:45], v[2:3], v[48:49], v[44:45]
	v_mov_b32_e32 v50, v47
	v_pk_fma_f32 v[44:45], v[8:9], v[50:51], v[44:45]
	s_nop 0
	v_add_f32_e32 v43, v42, v44
	v_add_f32_e32 v43, v43, v45
	ds_read_b128 v[44:47], v65 offset:736
	ds_read_b128 v[48:51], v65 offset:752
	s_waitcnt lgkmcnt(1)
	v_mov_b32_e32 v52, v44
	s_waitcnt lgkmcnt(0)
	v_mov_b32_e32 v53, v48
	v_mov_b32_e32 v48, v45
	v_pk_mul_f32 v[44:45], v[14:15], v[48:49]
	v_mov_b32_e32 v48, v46
	v_pk_fma_f32 v[44:45], v[12:13], v[52:53], v[44:45]
	v_mov_b32_e32 v49, v50
	v_pk_fma_f32 v[44:45], v[10:11], v[48:49], v[44:45]
	v_mov_b32_e32 v50, v47
	v_pk_fma_f32 v[44:45], v[16:17], v[50:51], v[44:45]
	s_nop 0
	v_add_f32_e32 v43, v43, v44
	v_add_f32_e32 v43, v43, v45
	v_min_f32_e32 v44, 0, v43
	v_mul_f32_e64 v43, |v43|, s82
	v_exp_f32_e32 v43, v43
	s_nop 0
	v_add_f32_e32 v43, 1.0, v43
	v_cmp_gt_f32_e32 vcc, s2, v43
	s_nop 1
	v_cndmask_b32_e64 v45, 0, 32, vcc
	v_ldexp_f32 v43, v43, v45
	v_log_f32_e32 v43, v43
	s_nop 0
	v_mul_f32_e32 v45, 0x3f317217, v43
	v_fma_f32 v45, v43, s85, -v45
	v_fmac_f32_e32 v45, 0x3377d1cf, v43
	v_fmac_f32_e32 v45, 0x3f317217, v43
	v_cmp_lt_f32_e64 s[42:43], |v43|, s83
	s_nop 1
	v_cndmask_b32_e64 v43, v43, v45, s[42:43]
	v_cndmask_b32_e32 v45, 0, v200, vcc
	v_sub_f32_e32 v43, v43, v45
	v_sub_f32_e32 v43, v44, v43
	ds_read_b128 v[44:47], v65 offset:768
	ds_read_b128 v[48:51], v65 offset:784
	v_fmamk_f32 v83, v43, 0x3d800000, v82
	s_waitcnt lgkmcnt(1)
	v_mov_b32_e32 v52, v44
	s_waitcnt lgkmcnt(0)
	v_mov_b32_e32 v53, v48
	v_mov_b32_e32 v48, v45
	v_pk_mul_f32 v[44:45], v[6:7], v[48:49]
	v_mov_b32_e32 v48, v46
	v_pk_fma_f32 v[44:45], v[4:5], v[52:53], v[44:45]
	v_mov_b32_e32 v49, v50
	v_pk_fma_f32 v[44:45], v[2:3], v[48:49], v[44:45]
	v_mov_b32_e32 v50, v47
	v_pk_fma_f32 v[44:45], v[8:9], v[50:51], v[44:45]
	s_nop 0
	v_add_f32_e32 v43, v42, v44
	v_add_f32_e32 v43, v43, v45
	ds_read_b128 v[44:47], v65 offset:800
	ds_read_b128 v[48:51], v65 offset:816
	s_waitcnt lgkmcnt(1)
	v_mov_b32_e32 v52, v44
	s_waitcnt lgkmcnt(0)
	v_mov_b32_e32 v53, v48
	v_mov_b32_e32 v48, v45
	v_pk_mul_f32 v[44:45], v[14:15], v[48:49]
	v_mov_b32_e32 v48, v46
	v_pk_fma_f32 v[44:45], v[12:13], v[52:53], v[44:45]
	v_mov_b32_e32 v49, v50
	v_pk_fma_f32 v[44:45], v[10:11], v[48:49], v[44:45]
	v_mov_b32_e32 v50, v47
	v_pk_fma_f32 v[44:45], v[16:17], v[50:51], v[44:45]
	s_nop 0
	v_add_f32_e32 v43, v43, v44
	v_add_f32_e32 v43, v43, v45
	v_min_f32_e32 v44, 0, v43
	v_mul_f32_e64 v43, |v43|, s82
	v_exp_f32_e32 v43, v43
	s_nop 0
	v_add_f32_e32 v43, 1.0, v43
	v_cmp_gt_f32_e32 vcc, s2, v43
	s_nop 1
	v_cndmask_b32_e64 v45, 0, 32, vcc
	v_ldexp_f32 v43, v43, v45
	v_log_f32_e32 v43, v43
	s_nop 0
	v_mul_f32_e32 v45, 0x3f317217, v43
	v_fma_f32 v45, v43, s85, -v45
	v_fmac_f32_e32 v45, 0x3377d1cf, v43
	v_fmac_f32_e32 v45, 0x3f317217, v43
	v_cmp_lt_f32_e64 s[42:43], |v43|, s83
	s_nop 1
	v_cndmask_b32_e64 v43, v43, v45, s[42:43]
	v_cndmask_b32_e32 v45, 0, v200, vcc
	v_sub_f32_e32 v43, v43, v45
	v_sub_f32_e32 v43, v44, v43
	ds_read_b128 v[44:47], v65 offset:832
	ds_read_b128 v[48:51], v65 offset:848
	v_fmamk_f32 v84, v43, 0x3d800000, v83
	s_waitcnt lgkmcnt(1)
	v_mov_b32_e32 v52, v44
	s_waitcnt lgkmcnt(0)
	v_mov_b32_e32 v53, v48
	v_mov_b32_e32 v48, v45
	v_pk_mul_f32 v[44:45], v[6:7], v[48:49]
	v_mov_b32_e32 v48, v46
	v_pk_fma_f32 v[44:45], v[4:5], v[52:53], v[44:45]
	v_mov_b32_e32 v49, v50
	v_pk_fma_f32 v[44:45], v[2:3], v[48:49], v[44:45]
	v_mov_b32_e32 v50, v47
	v_pk_fma_f32 v[44:45], v[8:9], v[50:51], v[44:45]
	s_nop 0
	v_add_f32_e32 v43, v42, v44
	v_add_f32_e32 v43, v43, v45
	ds_read_b128 v[44:47], v65 offset:864
	ds_read_b128 v[48:51], v65 offset:880
	s_waitcnt lgkmcnt(1)
	v_mov_b32_e32 v52, v44
	s_waitcnt lgkmcnt(0)
	v_mov_b32_e32 v53, v48
	v_mov_b32_e32 v48, v45
	v_pk_mul_f32 v[44:45], v[14:15], v[48:49]
	v_mov_b32_e32 v48, v46
	v_pk_fma_f32 v[44:45], v[12:13], v[52:53], v[44:45]
	v_mov_b32_e32 v49, v50
	v_pk_fma_f32 v[44:45], v[10:11], v[48:49], v[44:45]
	v_mov_b32_e32 v50, v47
	v_pk_fma_f32 v[44:45], v[16:17], v[50:51], v[44:45]
	s_nop 0
	v_add_f32_e32 v43, v43, v44
	v_add_f32_e32 v43, v43, v45
	v_min_f32_e32 v44, 0, v43
	v_mul_f32_e64 v43, |v43|, s82
	v_exp_f32_e32 v43, v43
	s_nop 0
	v_add_f32_e32 v43, 1.0, v43
	v_cmp_gt_f32_e32 vcc, s2, v43
	s_nop 1
	v_cndmask_b32_e64 v45, 0, 32, vcc
	v_ldexp_f32 v43, v43, v45
	v_log_f32_e32 v43, v43
	s_nop 0
	v_mul_f32_e32 v45, 0x3f317217, v43
	v_fma_f32 v45, v43, s85, -v45
	v_fmac_f32_e32 v45, 0x3377d1cf, v43
	v_fmac_f32_e32 v45, 0x3f317217, v43
	v_cmp_lt_f32_e64 s[42:43], |v43|, s83
	s_nop 1
	v_cndmask_b32_e64 v43, v43, v45, s[42:43]
	v_cndmask_b32_e32 v45, 0, v200, vcc
	v_sub_f32_e32 v43, v43, v45
	v_sub_f32_e32 v43, v44, v43
	ds_read_b128 v[44:47], v65 offset:896
	ds_read_b128 v[48:51], v65 offset:912
	v_fmamk_f32 v85, v43, 0x3d800000, v84
	s_waitcnt lgkmcnt(1)
	v_mov_b32_e32 v52, v44
	s_waitcnt lgkmcnt(0)
	v_mov_b32_e32 v53, v48
	v_mov_b32_e32 v48, v45
	v_pk_mul_f32 v[44:45], v[6:7], v[48:49]
	v_mov_b32_e32 v48, v46
	v_pk_fma_f32 v[44:45], v[4:5], v[52:53], v[44:45]
	v_mov_b32_e32 v49, v50
	v_pk_fma_f32 v[44:45], v[2:3], v[48:49], v[44:45]
	v_mov_b32_e32 v50, v47
	v_pk_fma_f32 v[44:45], v[8:9], v[50:51], v[44:45]
	s_nop 0
	v_add_f32_e32 v43, v42, v44
	v_add_f32_e32 v43, v43, v45
	ds_read_b128 v[44:47], v65 offset:928
	ds_read_b128 v[48:51], v65 offset:944
	s_waitcnt lgkmcnt(1)
	v_mov_b32_e32 v52, v44
	s_waitcnt lgkmcnt(0)
	v_mov_b32_e32 v53, v48
	v_mov_b32_e32 v48, v45
	v_pk_mul_f32 v[44:45], v[14:15], v[48:49]
	v_mov_b32_e32 v48, v46
	v_pk_fma_f32 v[44:45], v[12:13], v[52:53], v[44:45]
	v_mov_b32_e32 v49, v50
	v_pk_fma_f32 v[44:45], v[10:11], v[48:49], v[44:45]
	v_mov_b32_e32 v50, v47
	v_pk_fma_f32 v[44:45], v[16:17], v[50:51], v[44:45]
	s_nop 0
	v_add_f32_e32 v43, v43, v44
	v_add_f32_e32 v43, v43, v45
	v_min_f32_e32 v44, 0, v43
	v_mul_f32_e64 v43, |v43|, s82
	v_exp_f32_e32 v43, v43
	s_nop 0
	v_add_f32_e32 v43, 1.0, v43
	v_cmp_gt_f32_e32 vcc, s2, v43
	s_nop 1
	v_cndmask_b32_e64 v45, 0, 32, vcc
	v_ldexp_f32 v43, v43, v45
	v_log_f32_e32 v43, v43
	s_nop 0
	v_mul_f32_e32 v45, 0x3f317217, v43
	v_fma_f32 v45, v43, s85, -v45
	v_fmac_f32_e32 v45, 0x3377d1cf, v43
	v_fmac_f32_e32 v45, 0x3f317217, v43
	v_cmp_lt_f32_e64 s[42:43], |v43|, s83
	s_nop 1
	v_cndmask_b32_e64 v43, v43, v45, s[42:43]
	v_cndmask_b32_e32 v45, 0, v200, vcc
	v_sub_f32_e32 v43, v43, v45
	v_sub_f32_e32 v43, v44, v43
	ds_read_b128 v[44:47], v65 offset:960
	ds_read_b128 v[48:51], v65 offset:976
	v_fmamk_f32 v86, v43, 0x3d800000, v85
	s_waitcnt lgkmcnt(1)
	v_mov_b32_e32 v52, v44
	s_waitcnt lgkmcnt(0)
	v_mov_b32_e32 v53, v48
	v_mov_b32_e32 v48, v45
	v_pk_mul_f32 v[6:7], v[6:7], v[48:49]
	s_nop 0
	v_pk_fma_f32 v[4:5], v[4:5], v[52:53], v[6:7]
	v_mov_b32_e32 v6, v46
	v_mov_b32_e32 v7, v50
	v_pk_fma_f32 v[2:3], v[2:3], v[6:7], v[4:5]
	v_mov_b32_e32 v50, v47
	v_pk_fma_f32 v[2:3], v[8:9], v[50:51], v[2:3]
	s_nop 0
	v_add_f32_e32 v2, v42, v2
	v_add_f32_e32 v44, v2, v3
	ds_read_b128 v[2:5], v65 offset:992
	ds_read_b128 v[6:9], v65 offset:1008
	s_waitcnt lgkmcnt(1)
	v_mov_b32_e32 v42, v2
	s_waitcnt lgkmcnt(0)
	v_mov_b32_e32 v43, v6
	v_mov_b32_e32 v6, v3
	v_pk_mul_f32 v[2:3], v[14:15], v[6:7]
	v_mov_b32_e32 v6, v4
	v_pk_fma_f32 v[2:3], v[12:13], v[42:43], v[2:3]
	v_mov_b32_e32 v7, v8
	v_pk_fma_f32 v[2:3], v[10:11], v[6:7], v[2:3]
	v_mov_b32_e32 v8, v5
	v_pk_fma_f32 v[2:3], v[16:17], v[8:9], v[2:3]
	s_nop 0
	v_add_f32_e32 v2, v44, v2
	v_add_f32_e32 v2, v2, v3
	v_min_f32_e32 v3, 0, v2
	v_mul_f32_e64 v2, |v2|, s82
	v_exp_f32_e32 v2, v2
	s_nop 0
	v_add_f32_e32 v2, 1.0, v2
	v_cmp_gt_f32_e32 vcc, s2, v2
	s_nop 1
	v_cndmask_b32_e64 v4, 0, 32, vcc
	v_ldexp_f32 v2, v2, v4
	v_log_f32_e32 v2, v2
	s_nop 0
	v_mul_f32_e32 v4, 0x3f317217, v2
	v_fma_f32 v4, v2, s85, -v4
	v_fmac_f32_e32 v4, 0x3377d1cf, v2
	v_fmac_f32_e32 v4, 0x3f317217, v2
	v_cmp_lt_f32_e64 s[42:43], |v2|, s83
	s_nop 1
	v_cndmask_b32_e64 v2, v2, v4, s[42:43]
	v_cndmask_b32_e32 v4, 0, v200, vcc
	v_sub_f32_e32 v2, v2, v4
	v_sub_f32_e32 v2, v3, v2
	v_fmamk_f32 v87, v2, 0x3d800000, v86
	ds_write_b32 v28, v87 offset:4096
.LBB0_244:
	s_or_b64 exec, exec, s[44:45]
	s_waitcnt lgkmcnt(0)
	s_barrier
	s_and_saveexec_b64 s[42:43], s[4:5]
	s_cbranch_execz .LBB0_247
	s_waitcnt vmcnt(0)
	v_mov_b32_e32 v2, v202
	v_mov_b32_e32 v3, v203
	v_mov_b32_e32 v4, v204
	v_mov_b32_e32 v5, v205
	v_mov_b32_e32 v6, v206
	v_mov_b32_e32 v7, v207
	v_mov_b32_e32 v8, v208
	v_mov_b32_e32 v9, v209
	v_mov_b32_e32 v10, v210
	v_mov_b32_e32 v11, v211
	v_mov_b32_e32 v12, v212
	v_mov_b32_e32 v13, v213
	v_mov_b32_e32 v14, v214
	v_mov_b32_e32 v15, v215
	v_mov_b32_e32 v16, v216
	v_mov_b32_e32 v17, v217
	v_mov_b32_e32 v42, v218
	v_mov_b32_e32 v43, v219
	v_mov_b32_e32 v44, v220
	v_mov_b32_e32 v45, v221
	v_mov_b32_e32 v46, v222
	v_mov_b32_e32 v47, v223
	v_mov_b32_e32 v48, v224
	v_mov_b32_e32 v49, v225
	v_mov_b32_e32 v50, v226
	v_mov_b32_e32 v51, v227
	v_mov_b32_e32 v52, v228
	v_mov_b32_e32 v53, v229
	v_mov_b32_e32 v54, v230
	v_mov_b32_e32 v55, v231
	v_mov_b32_e32 v56, v232
	v_mov_b32_e32 v57, v233
	v_mov_b32_e32 v58, v234
	v_mov_b32_e32 v59, v235
	v_mov_b32_e32 v90, v236
	v_mov_b32_e32 v91, v237
	v_mov_b32_e32 v94, v144
	v_mov_b32_e32 v95, v145
	v_mov_b32_e32 v96, v146
	v_mov_b32_e32 v97, v147
	v_mov_b32_e32 v98, v148
	v_mov_b32_e32 v99, v149
	v_mov_b32_e32 v100, v150
	v_mov_b32_e32 v101, v151
	v_mov_b32_e32 v102, v152
	v_mov_b32_e32 v103, v153
	v_mov_b32_e32 v104, v154
	v_mov_b32_e32 v105, v155
	v_mov_b32_e32 v106, v156
	v_mov_b32_e32 v107, v157
	v_mov_b32_e32 v108, v158
	v_mov_b32_e32 v109, v159
	v_mov_b32_e32 v110, v178
	v_mov_b32_e32 v111, v179
	v_mov_b32_e32 v112, v180
	v_mov_b32_e32 v113, v181
	v_mov_b32_e32 v114, v182
	v_mov_b32_e32 v115, v183
	v_mov_b32_e32 v116, v184
	v_mov_b32_e32 v117, v185
	v_mov_b32_e32 v118, v186
	v_mov_b32_e32 v119, v187
	v_mov_b32_e32 v120, v188
	v_mov_b32_e32 v121, v189
	v_mov_b32_e32 v122, v190
	v_mov_b32_e32 v123, v191
	v_mov_b32_e32 v124, v238
	v_mov_b32_e32 v125, v239
	v_add_u32_e32 v88, 0x1000, v26
	ds_read2_b32 v[88:89], v88 offset1:96
	v_add_u32_e32 v92, 0x1200, v26
	ds_read2_b32 v[92:93], v92 offset0:64 offset1:160
	s_waitcnt vmcnt(25)
	s_waitcnt lgkmcnt(1)
	v_cndmask_b32_e64 v126, 0, v88, s[6:7]
	v_cndmask_b32_e64 v127, 0, v89, s[36:37]
	v_add_f32_e32 v126, v126, v127
	s_waitcnt lgkmcnt(0)
	v_cndmask_b32_e64 v127, 0, v92, s[38:39]
	v_add_f32_e32 v126, v126, v127
	v_add_f32_e32 v92, v92, v93
	v_add_f32_e32 v88, v88, v89
	s_waitcnt vmcnt(24)
	s_waitcnt vmcnt(17)
	s_waitcnt vmcnt(16)
	s_waitcnt vmcnt(9)
	s_waitcnt vmcnt(8)
	s_waitcnt vmcnt(1)
	s_waitcnt vmcnt(0)
	v_add_f32_e32 v89, v88, v92
	v_add_f32_e32 v92, v72, v126
	v_lshlrev_b32_e32 v93, 16, v94
	v_lshlrev_b32_e32 v94, 16, v95
	v_lshlrev_b32_e32 v95, 16, v96
	v_lshlrev_b32_e32 v96, 16, v97
	v_lshlrev_b32_e32 v97, 16, v98
	v_lshlrev_b32_e32 v98, 16, v99
	v_lshlrev_b32_e32 v99, 16, v100
	v_lshlrev_b32_e32 v100, 16, v101
	v_lshlrev_b32_e32 v101, 16, v102
	v_lshlrev_b32_e32 v102, 16, v103
	v_lshlrev_b32_e32 v103, 16, v104
	v_lshlrev_b32_e32 v104, 16, v105
	v_lshlrev_b32_e32 v105, 16, v106
	v_lshlrev_b32_e32 v106, 16, v107
	v_lshlrev_b32_e32 v107, 16, v108
	v_lshlrev_b32_e32 v108, 16, v109
	v_lshlrev_b32_e32 v109, 16, v110
	v_lshlrev_b32_e32 v110, 16, v111
	v_lshlrev_b32_e32 v111, 16, v112
	v_lshlrev_b32_e32 v112, 16, v113
	v_lshlrev_b32_e32 v113, 16, v114
	v_lshlrev_b32_e32 v114, 16, v115
	v_lshlrev_b32_e32 v115, 16, v116
	v_lshlrev_b32_e32 v116, 16, v117
	v_lshlrev_b32_e32 v117, 16, v118
	v_lshlrev_b32_e32 v118, 16, v119
	v_lshlrev_b32_e32 v119, 16, v120
	v_lshlrev_b32_e32 v120, 16, v121
	v_lshlrev_b32_e32 v121, 16, v122
	v_lshlrev_b32_e32 v122, 16, v123
	v_lshlrev_b32_e32 v123, 16, v124
	v_lshlrev_b32_e32 v124, 16, v125
	v_sub_f32_e32 v125, v92, v88
	v_mul_f32_e32 v125, 0x3fb8aa3b, v125
	v_exp_f32_e32 v125, v125
	v_sub_f32_e32 v127, v88, v92
	v_mul_f32_e32 v127, 0x3fb8aa3b, v127
	v_sub_f32_e32 v92, v89, v92
	v_exp_f32_e32 v127, v127
	v_mul_f32_e32 v92, 0x3fb8aa3b, v92
	v_exp_f32_e32 v92, v92
	v_mul_f32_e32 v93, v125, v93
	v_cvt_pk_bf16_f32 v93, v93, v1
	global_store_short v[90:91], v93, off offset:2048
	v_mul_f32_e32 v93, v127, v94
	v_cvt_pk_bf16_f32 v93, v93, v1
	global_store_short v[90:91], v93, off offset:2816
	v_mul_f32_e32 v90, v92, v94
	v_cvt_pk_bf16_f32 v90, v90, v1
	ds_write_b16 v71, v90 offset:8192
	v_add_f32_e32 v90, v73, v126
	v_sub_f32_e32 v91, v90, v88
	v_mul_f32_e32 v91, 0x3fb8aa3b, v91
	v_exp_f32_e32 v91, v91
	v_sub_f32_e32 v92, v88, v90
	v_mul_f32_e32 v92, 0x3fb8aa3b, v92
	v_sub_f32_e32 v90, v89, v90
	v_exp_f32_e32 v92, v92
	v_mul_f32_e32 v90, 0x3fb8aa3b, v90
	v_exp_f32_e32 v90, v90
	v_mul_f32_e32 v91, v91, v95
	v_cvt_pk_bf16_f32 v91, v91, v1
	global_store_short v[58:59], v91, off offset:512
	v_mul_f32_e32 v91, v92, v96
	v_cvt_pk_bf16_f32 v91, v91, v1
	global_store_short v[58:59], v91, off offset:1280
	v_mul_f32_e32 v58, v90, v96
	v_cvt_pk_bf16_f32 v58, v58, v1
	ds_write_b16 v71, v58 offset:8400
	v_add_f32_e32 v58, v74, v126
	v_sub_f32_e32 v59, v58, v88
	v_mul_f32_e32 v59, 0x3fb8aa3b, v59
	v_exp_f32_e32 v59, v59
	v_sub_f32_e32 v90, v88, v58
	v_mul_f32_e32 v90, 0x3fb8aa3b, v90
	v_sub_f32_e32 v58, v89, v58
	v_exp_f32_e32 v90, v90
	v_mul_f32_e32 v58, 0x3fb8aa3b, v58
	v_exp_f32_e32 v58, v58
	v_mul_f32_e32 v59, v59, v97
	v_cvt_pk_bf16_f32 v59, v59, v1
	global_store_short v[56:57], v59, off offset:3072
	v_mul_f32_e32 v59, v90, v98
	v_cvt_pk_bf16_f32 v59, v59, v1
	global_store_short v[56:57], v59, off offset:3840
	v_mul_f32_e32 v56, v58, v98
	v_cvt_pk_bf16_f32 v56, v56, v1
	ds_write_b16 v71, v56 offset:8608
	v_add_f32_e32 v56, v75, v126
	v_sub_f32_e32 v57, v56, v88
	v_mul_f32_e32 v57, 0x3fb8aa3b, v57
	v_exp_f32_e32 v57, v57
	v_sub_f32_e32 v58, v88, v56
	v_mul_f32_e32 v58, 0x3fb8aa3b, v58
	v_sub_f32_e32 v56, v89, v56
	v_exp_f32_e32 v58, v58
	v_mul_f32_e32 v56, 0x3fb8aa3b, v56
	v_exp_f32_e32 v56, v56
	v_mul_f32_e32 v57, v57, v99
	v_cvt_pk_bf16_f32 v57, v57, v1
	global_store_short v[54:55], v57, off offset:1536
	v_mul_f32_e32 v57, v58, v100
	v_cvt_pk_bf16_f32 v57, v57, v1
	global_store_short v[54:55], v57, off offset:2304
	v_mul_f32_e32 v54, v56, v100
	v_cvt_pk_bf16_f32 v54, v54, v1
	ds_write_b16 v71, v54 offset:8816
	v_add_f32_e32 v54, v76, v126
	v_sub_f32_e32 v55, v54, v88
	v_mul_f32_e32 v55, 0x3fb8aa3b, v55
	v_exp_f32_e32 v55, v55
	v_sub_f32_e32 v56, v88, v54
	v_mul_f32_e32 v56, 0x3fb8aa3b, v56
	v_sub_f32_e32 v54, v89, v54
	v_exp_f32_e32 v56, v56
	v_mul_f32_e32 v54, 0x3fb8aa3b, v54
	v_exp_f32_e32 v54, v54
	v_mul_f32_e32 v55, v55, v101
	v_cvt_pk_bf16_f32 v55, v55, v1
	global_store_short v[52:53], v55, off
	v_mul_f32_e32 v55, v56, v102
	v_cvt_pk_bf16_f32 v55, v55, v1
	global_store_short v[52:53], v55, off offset:768
	v_mul_f32_e32 v52, v54, v102
	v_cvt_pk_bf16_f32 v52, v52, v1
	ds_write_b16 v71, v52 offset:9024
	v_add_f32_e32 v52, v77, v126
	v_sub_f32_e32 v53, v52, v88
	v_mul_f32_e32 v53, 0x3fb8aa3b, v53
	v_exp_f32_e32 v53, v53
	v_sub_f32_e32 v54, v88, v52
	v_mul_f32_e32 v54, 0x3fb8aa3b, v54
	v_sub_f32_e32 v52, v89, v52
	v_exp_f32_e32 v54, v54
	v_mul_f32_e32 v52, 0x3fb8aa3b, v52
	v_exp_f32_e32 v52, v52
	v_mul_f32_e32 v53, v53, v103
	v_cvt_pk_bf16_f32 v53, v53, v1
	global_store_short v[50:51], v53, off offset:2560
	v_mul_f32_e32 v53, v54, v104
	v_cvt_pk_bf16_f32 v53, v53, v1
	global_store_short v[50:51], v53, off offset:3328
	v_mul_f32_e32 v50, v52, v104
	v_cvt_pk_bf16_f32 v50, v50, v1
	ds_write_b16 v71, v50 offset:9232
	v_add_f32_e32 v50, v78, v126
	v_sub_f32_e32 v51, v50, v88
	v_mul_f32_e32 v51, 0x3fb8aa3b, v51
	v_exp_f32_e32 v51, v51
	v_sub_f32_e32 v52, v88, v50
	v_mul_f32_e32 v52, 0x3fb8aa3b, v52
	v_sub_f32_e32 v50, v89, v50
	v_exp_f32_e32 v52, v52
	v_mul_f32_e32 v50, 0x3fb8aa3b, v50
	v_exp_f32_e32 v50, v50
	v_mul_f32_e32 v51, v51, v105
	v_cvt_pk_bf16_f32 v51, v51, v1
	global_store_short v[48:49], v51, off offset:1024
	v_mul_f32_e32 v51, v52, v106
	v_cvt_pk_bf16_f32 v51, v51, v1
	global_store_short v[48:49], v51, off offset:1792
	v_mul_f32_e32 v48, v50, v106
	v_cvt_pk_bf16_f32 v48, v48, v1
	ds_write_b16 v71, v48 offset:9440
	v_add_f32_e32 v48, v79, v126
	v_sub_f32_e32 v49, v48, v88
	v_mul_f32_e32 v49, 0x3fb8aa3b, v49
	v_sub_f32_e32 v50, v88, v48
	v_exp_f32_e32 v49, v49
	v_mul_f32_e32 v50, 0x3fb8aa3b, v50
	v_exp_f32_e32 v50, v50
	v_sub_f32_e32 v48, v89, v48
	v_mul_f32_e32 v48, 0x3fb8aa3b, v48
	v_exp_f32_e32 v48, v48
	v_mul_f32_e32 v49, v49, v107
	v_cvt_pk_bf16_f32 v49, v49, v1
	global_store_short v[44:45], v49, off offset:3584
	v_mul_f32_e32 v44, v50, v108
	v_cvt_pk_bf16_f32 v44, v44, v1
	global_store_short v[46:47], v44, off offset:256
	v_mul_f32_e32 v44, v48, v108
	v_cvt_pk_bf16_f32 v44, v44, v1
	ds_write_b16 v71, v44 offset:9648
	v_add_f32_e32 v44, v80, v126
	v_sub_f32_e32 v45, v44, v88
	v_mul_f32_e32 v45, 0x3fb8aa3b, v45
	v_exp_f32_e32 v45, v45
	v_sub_f32_e32 v46, v88, v44
	v_mul_f32_e32 v46, 0x3fb8aa3b, v46
	v_sub_f32_e32 v44, v89, v44
	v_exp_f32_e32 v46, v46
	v_mul_f32_e32 v44, 0x3fb8aa3b, v44
	v_exp_f32_e32 v44, v44
	v_mul_f32_e32 v45, v45, v109
	v_cvt_pk_bf16_f32 v45, v45, v1
	global_store_short v[42:43], v45, off offset:2048
	v_mul_f32_e32 v45, v46, v110
	v_cvt_pk_bf16_f32 v45, v45, v1
	global_store_short v[42:43], v45, off offset:2816
	v_mul_f32_e32 v42, v44, v110
	v_cvt_pk_bf16_f32 v42, v42, v1
	ds_write_b16 v71, v42 offset:9856
	v_add_f32_e32 v42, v81, v126
	v_sub_f32_e32 v43, v42, v88
	v_mul_f32_e32 v43, 0x3fb8aa3b, v43
	v_exp_f32_e32 v43, v43
	v_sub_f32_e32 v44, v88, v42
	v_mul_f32_e32 v44, 0x3fb8aa3b, v44
	v_sub_f32_e32 v42, v89, v42
	v_exp_f32_e32 v44, v44
	v_mul_f32_e32 v42, 0x3fb8aa3b, v42
	v_exp_f32_e32 v42, v42
	v_mul_f32_e32 v43, v43, v111
	v_cvt_pk_bf16_f32 v43, v43, v1
	global_store_short v[16:17], v43, off offset:512
	v_mul_f32_e32 v43, v44, v112
	v_cvt_pk_bf16_f32 v43, v43, v1
	global_store_short v[16:17], v43, off offset:1280
	v_mul_f32_e32 v16, v42, v112
	v_cvt_pk_bf16_f32 v16, v16, v1
	ds_write_b16 v71, v16 offset:10064
	v_add_f32_e32 v16, v82, v126
	v_sub_f32_e32 v17, v16, v88
	v_mul_f32_e32 v17, 0x3fb8aa3b, v17
	v_exp_f32_e32 v17, v17
	v_sub_f32_e32 v42, v88, v16
	v_mul_f32_e32 v42, 0x3fb8aa3b, v42
	v_sub_f32_e32 v16, v89, v16
	v_exp_f32_e32 v42, v42
	v_mul_f32_e32 v16, 0x3fb8aa3b, v16
	v_exp_f32_e32 v16, v16
	v_mul_f32_e32 v17, v17, v113
	v_cvt_pk_bf16_f32 v17, v17, v1
	global_store_short v[14:15], v17, off offset:3072
	v_mul_f32_e32 v17, v42, v114
	v_cvt_pk_bf16_f32 v17, v17, v1
	global_store_short v[14:15], v17, off offset:3840
	v_mul_f32_e32 v14, v16, v114
	v_cvt_pk_bf16_f32 v14, v14, v1
	ds_write_b16 v71, v14 offset:10272
	v_add_f32_e32 v14, v83, v126
	v_sub_f32_e32 v15, v14, v88
	v_mul_f32_e32 v15, 0x3fb8aa3b, v15
	v_exp_f32_e32 v15, v15
	v_sub_f32_e32 v16, v88, v14
	v_mul_f32_e32 v16, 0x3fb8aa3b, v16
	v_sub_f32_e32 v14, v89, v14
	v_exp_f32_e32 v16, v16
	v_mul_f32_e32 v14, 0x3fb8aa3b, v14
	v_exp_f32_e32 v14, v14
	v_mul_f32_e32 v15, v15, v115
	v_cvt_pk_bf16_f32 v15, v15, v1
	global_store_short v[12:13], v15, off offset:1536
	v_mul_f32_e32 v15, v16, v116
	v_cvt_pk_bf16_f32 v15, v15, v1
	global_store_short v[12:13], v15, off offset:2304
	v_mul_f32_e32 v12, v14, v116
	v_cvt_pk_bf16_f32 v12, v12, v1
	ds_write_b16 v71, v12 offset:10480
	v_add_f32_e32 v12, v84, v126
	v_sub_f32_e32 v13, v12, v88
	v_mul_f32_e32 v13, 0x3fb8aa3b, v13
	v_exp_f32_e32 v13, v13
	v_sub_f32_e32 v14, v88, v12
	v_mul_f32_e32 v14, 0x3fb8aa3b, v14
	v_sub_f32_e32 v12, v89, v12
	v_exp_f32_e32 v14, v14
	v_mul_f32_e32 v12, 0x3fb8aa3b, v12
	v_exp_f32_e32 v12, v12
	v_mul_f32_e32 v13, v13, v117
	v_cvt_pk_bf16_f32 v13, v13, v1
	global_store_short v[10:11], v13, off
	v_mul_f32_e32 v13, v14, v118
	v_cvt_pk_bf16_f32 v13, v13, v1
	global_store_short v[10:11], v13, off offset:768
	v_mul_f32_e32 v10, v12, v118
	v_cvt_pk_bf16_f32 v10, v10, v1
	ds_write_b16 v71, v10 offset:10688
	v_add_f32_e32 v10, v85, v126
	v_sub_f32_e32 v11, v10, v88
	v_mul_f32_e32 v11, 0x3fb8aa3b, v11
	v_exp_f32_e32 v11, v11
	v_sub_f32_e32 v12, v88, v10
	v_mul_f32_e32 v12, 0x3fb8aa3b, v12
	v_sub_f32_e32 v10, v89, v10
	v_exp_f32_e32 v12, v12
	v_mul_f32_e32 v10, 0x3fb8aa3b, v10
	v_exp_f32_e32 v10, v10
	v_mul_f32_e32 v11, v11, v119
	v_cvt_pk_bf16_f32 v11, v11, v1
	global_store_short v[8:9], v11, off offset:2560
	v_mul_f32_e32 v11, v12, v120
	v_cvt_pk_bf16_f32 v11, v11, v1
	global_store_short v[8:9], v11, off offset:3328
	v_mul_f32_e32 v8, v10, v120
	v_cvt_pk_bf16_f32 v8, v8, v1
	ds_write_b16 v71, v8 offset:10896
	v_add_f32_e32 v8, v86, v126
	v_sub_f32_e32 v9, v8, v88
	v_mul_f32_e32 v9, 0x3fb8aa3b, v9
	v_exp_f32_e32 v9, v9
	v_sub_f32_e32 v10, v88, v8
	v_mul_f32_e32 v10, 0x3fb8aa3b, v10
	v_sub_f32_e32 v8, v89, v8
	v_exp_f32_e32 v10, v10
	v_mul_f32_e32 v8, 0x3fb8aa3b, v8
	v_exp_f32_e32 v8, v8
	v_mul_f32_e32 v9, v9, v121
	v_cvt_pk_bf16_f32 v9, v9, v1
	global_store_short v[6:7], v9, off offset:1024
	v_mul_f32_e32 v9, v10, v122
	v_cvt_pk_bf16_f32 v9, v9, v1
	global_store_short v[6:7], v9, off offset:1792
	v_mul_f32_e32 v6, v8, v122
	v_cvt_pk_bf16_f32 v6, v6, v1
	ds_write_b16 v71, v6 offset:11104
	v_add_f32_e32 v6, v87, v126
	v_sub_f32_e32 v7, v6, v88
	v_mul_f32_e32 v7, 0x3fb8aa3b, v7
	v_sub_f32_e32 v8, v88, v6
	v_exp_f32_e32 v7, v7
	v_mul_f32_e32 v8, 0x3fb8aa3b, v8
	v_exp_f32_e32 v8, v8
	v_sub_f32_e32 v6, v89, v6
	v_mul_f32_e32 v6, 0x3fb8aa3b, v6
	v_exp_f32_e32 v6, v6
	v_mul_f32_e32 v7, v7, v123
	v_cvt_pk_bf16_f32 v7, v7, v1
	global_store_short v[2:3], v7, off offset:3584
	v_mul_f32_e32 v2, v8, v124
	v_cvt_pk_bf16_f32 v2, v2, v1
	global_store_short v[4:5], v2, off offset:256
	v_mul_f32_e32 v2, v6, v124
	v_cvt_pk_bf16_f32 v2, v2, v1
	ds_write_b16 v71, v2 offset:11312
	s_and_b64 exec, exec, s[40:41]
	s_cbranch_execz .LBB0_247
	v_mul_f32_e32 v2, 0x3fb8aa3b, v89
	v_exp_f32_e32 v6, v2
	s_mul_i32 s14, s47, 0x60
	v_add_u32_e32 v2, s14, v24
	v_ashrrev_i32_e32 v3, 31, v2
	v_lshl_add_u64 v[4:5], v[2:3], 2, s[80:81]
	v_mul_f32_e32 v3, 0x3fb8aa3b, v88
	global_store_dword v[4:5], v6, off
	v_exp_f32_e32 v4, v3
	v_add_u32_e32 v2, 0xc000, v2
	v_ashrrev_i32_e32 v3, 31, v2
	v_lshl_add_u64 v[2:3], v[2:3], 2, s[80:81]
	global_store_dword v[2:3], v4, off
